# v004 plus: MLP-down walks each XCD's four 8-row-tile groups in reverse (row tile pm^24), so the u rows MLP-up wrote last are read first
# speedup vs baseline: 1.0162x; 1.0025x over previous
.LBB0_613:
	s_or_b64 exec, exec, s[4:5]
	v_readlane_b32 s4, v254, 42
	v_readlane_b32 s5, v254, 43
	s_add_u32 s0, s4, s6
	v_readlane_b32 s14, v254, 36
	s_addc_u32 s4, s5, s7
	v_readlane_b32 s15, v254, 37
	s_add_u32 s18, s0, 0x80000
	s_mov_b32 s15, s1
	s_addc_u32 s19, s4, 0
	s_mov_b64 s[12:13], s[82:83]
	s_mov_b64 s[4:5], s[82:83]
	v_writelane_b32 v254, s14, 36
	s_mov_b64 s[42:43], s[82:83]
	s_mov_b64 s[40:41], s[82:83]
	v_mov_b32_e32 v16, v224
	s_waitcnt lgkmcnt(0)
	s_barrier
	v_writelane_b32 v254, s15, 37
	s_and_b64 vcc, exec, s[38:39]
	v_readfirstlane_b32 s20, v16
	s_cbranch_vccnz .LBB0_649
	v_lshlrev_b32_e32 v0, 4, v16
	v_add_u32_e32 v2, 0x2000, v0
	v_ashrrev_i32_e32 v3, 31, v2
	v_lshrrev_b32_e32 v3, 22, v3
	v_add_u32_e32 v3, v2, v3
	v_ashrrev_i32_e32 v10, 10, v3
	v_mul_i32_i24_e32 v3, 0x400, v10
	v_sub_u32_e32 v2, v2, v3
	v_lshrrev_b32_e32 v3, 4, v2
	s_add_u32 s0, s12, 0x18000000
	v_bitop3_b32 v2, v3, v2, 32 bitop3:0x6c
	s_addc_u32 s17, s13, 0
	v_readlane_b32 s12, v254, 36
	v_ashrrev_i32_e32 v3, 31, v2
	v_readlane_b32 s13, v254, 37
	v_lshrrev_b32_e32 v3, 26, v3
	s_lshl_b64 s[12:13], s[12:13], 23
	v_add_u32_e32 v3, v2, v3
	v_lshlrev_b32_e32 v4, 3, v10
	s_add_u32 s4, s4, s12
	v_ashrrev_i32_e32 v11, 6, v3
	v_and_b32_e32 v4, -16, v4
	s_addc_u32 s5, s5, s13
	v_add_u32_e32 v4, v11, v4
	s_add_u32 s60, s4, 0x2400000
	v_and_b32_e32 v5, 3, v11
	s_mov_b32 s4, 0x7ffe0
	v_lshrrev_b32_e32 v6, 2, v4
	v_lshlrev_b32_e32 v7, 1, v4
	v_and_or_b32 v5, v4, s4, v5
	v_and_b32_e32 v6, 4, v6
	v_and_b32_e32 v7, 24, v7
	v_and_b32_e32 v3, 0xc0, v3
	v_or3_b32 v5, v5, v6, v7
	v_sub_u32_e32 v2, v2, v3
	v_mov_b32_e32 v7, 1
	v_lshlrev_b32_e32 v6, 5, v10
	v_ashrrev_i16_sdwa v2, v7, sext(v2) dst_sel:DWORD dst_unused:UNUSED_PAD src0_sel:DWORD src1_sel:BYTE_0
	v_and_b32_e32 v6, 32, v6
	v_bfe_i32 v12, v2, 0, 16
	v_add_lshl_u32 v2, v6, v12, 1
	s_waitcnt vmcnt(0)
	v_lshl_add_u32 v154, v5, 13, v2
	v_lshl_add_u32 v156, v4, 13, v2
	v_bfe_i32 v2, v16, 27, 1
	v_lshrrev_b32_e32 v2, 22, v2
	v_add_u32_e32 v2, v0, v2
	v_and_b32_e32 v2, 0xfffffc00, v2
	v_sub_u32_e32 v0, v0, v2
	v_lshrrev_b32_e32 v2, 4, v0
	v_ashrrev_i32_e32 v3, 31, v16
	v_bitop3_b32 v0, v2, v0, 32 bitop3:0x6c
	v_lshrrev_b32_e32 v3, 26, v3
	v_ashrrev_i32_e32 v2, 31, v0
	v_add_u32_e32 v3, v16, v3
	v_lshrrev_b32_e32 v2, 26, v2
	v_ashrrev_i32_e32 v14, 6, v3
	v_add_u32_e32 v2, v0, v2
	v_lshlrev_b32_e32 v3, 3, v14
	v_ashrrev_i32_e32 v13, 6, v2
	v_and_b32_e32 v3, -16, v3
	v_add_u32_e32 v3, v13, v3
	v_and_b32_e32 v4, 3, v13
	v_lshrrev_b32_e32 v5, 2, v3
	v_lshlrev_b32_e32 v6, 1, v3
	v_and_b32_e32 v2, 0xc0, v2
	s_addc_u32 s61, s5, 0
	s_ashr_i32 s21, s20, 6
	v_and_or_b32 v4, v3, s4, v4
	v_and_b32_e32 v5, 4, v5
	v_and_b32_e32 v6, 24, v6
	v_sub_u32_e32 v0, v0, v2
	s_ashr_i32 s28, s20, 8
	s_lshl_b32 s62, s21, 10
	v_or3_b32 v4, v4, v5, v6
	v_lshlrev_b32_e32 v5, 5, v14
	v_ashrrev_i16_sdwa v0, v7, sext(v0) dst_sel:DWORD dst_unused:UNUSED_PAD src0_sel:DWORD src1_sel:BYTE_0
	v_readlane_b32 s4, v254, 17
	v_and_b32_e32 v5, 32, v5
	v_bfe_i32 v15, v0, 0, 16
	v_readlane_b32 s5, v254, 18
	s_add_u32 s12, s60, s4
	v_add_lshl_u32 v2, v5, v15, 1
	s_addc_u32 s13, s61, s5
	s_add_i32 s63, s62, 0
	v_lshl_add_u32 v0, v4, 13, v2
	s_add_i32 m0, s63, 0x10000
	v_lshl_add_u32 v158, v3, 13, v2
	global_load_lds_dwordx4 v0, s[12:13]
	s_add_i32 m0, s63, 0x12000
	s_add_u32 s4, s12, 0x100000
	global_load_lds_dwordx4 v154, s[12:13]
	s_addc_u32 s5, s13, 0
	s_add_i32 m0, s63, 0x14000
	v_mov_b32_e32 v155, v1
	global_load_lds_dwordx4 v0, s[4:5]
	s_add_i32 m0, s63, 0x16000
	v_mov_b32_e32 v159, v1
	global_load_lds_dwordx4 v154, s[4:5]
	v_readlane_b32 s4, v254, 13
	s_xor_b32 s4, s4, 0x3000000
	v_readlane_b32 s5, v254, 14
	s_add_u32 s14, s0, s4
	s_addc_u32 s15, s17, s5
	s_add_i32 s64, s63, 0x2000
	s_mov_b32 m0, s63
	s_add_u32 s4, s14, 0x100000
	global_load_lds_dwordx4 v158, s[14:15]
	s_mov_b32 m0, s64
	s_addc_u32 s5, s15, 0
	s_add_i32 s65, s63, 0x4000
	global_load_lds_dwordx4 v156, s[14:15]
	s_mov_b32 m0, s65
	s_add_i32 s66, s63, 0x6000
	global_load_lds_dwordx4 v158, s[4:5]
	s_mov_b32 m0, s66
	v_mov_b32_e32 v157, v1
	global_load_lds_dwordx4 v156, s[4:5]
	s_cmp_eq_u32 s28, 1
	v_lshl_add_u64 v[8:9], s[12:13], 0, v[0:1]
	v_lshl_add_u64 v[6:7], s[12:13], 0, v[154:155]
	v_lshl_add_u64 v[2:3], s[14:15], 0, v[158:159]
	s_cselect_b64 s[4:5], -1, 0
	s_cmp_lg_u32 s28, 1
	v_lshl_add_u64 v[4:5], s[14:15], 0, v[156:157]
	s_cbranch_scc1 .LBB0_616
	s_barrier
.LBB0_616:
	s_add_u32 s44, s42, 0x4000000
	s_addc_u32 s45, s43, 0
	s_add_u32 s46, s40, 0x4000000
	v_bfe_u32 v17, v16, 4, 2
	s_addc_u32 s47, s41, 0
	v_and_b32_e32 v18, 15, v16
	v_lshlrev_b32_e32 v19, 4, v17
	v_lshlrev_b32_e32 v16, 2, v16
	s_lshl_b32 s21, s21, 5
	v_lshl_or_b32 v182, s28, 6, v18
	v_lshl_or_b32 v18, v18, 6, v19
	s_lshl_b32 s28, s28, 13
	v_and_b32_e32 v16, 32, v16
	s_and_b32 s21, s21, 0x60
	s_add_i32 m0, s63, 0x18000
	v_lshl_add_u64 v[8:9], v[8:9], 0, s[10:11]
	v_bitop3_b32 v19, v18, s28, v16 bitop3:0xde
	s_lshl_b32 s28, s21, 7
	s_waitcnt vmcnt(2)
	s_barrier
	global_load_lds_dwordx4 v[8:9], off
	v_lshl_add_u64 v[6:7], v[6:7], 0, s[10:11]
	s_add_i32 m0, s63, 0x1a000
	s_add_i32 s67, s63, 0x8000
	s_add_i32 s68, s63, 0xa000
	v_bitop3_b32 v183, v18, s28, v16 bitop3:0xde
	global_load_lds_dwordx4 v[6:7], off
	v_lshl_add_u64 v[2:3], v[2:3], 0, s[10:11]
	s_mov_b32 m0, s67
	s_add_u32 s28, s12, 0x100080
	global_load_lds_dwordx4 v[2:3], off
	v_lshl_add_u64 v[2:3], v[4:5], 0, s[10:11]
	s_mov_b32 m0, s68
	s_addc_u32 s29, s13, 0
	global_load_lds_dwordx4 v[2:3], off
	s_add_i32 m0, s63, 0x1c000
	v_lshl_add_u64 v[2:3], s[28:29], 0, v[0:1]
	global_load_lds_dwordx4 v[2:3], off
	v_lshl_add_u64 v[2:3], s[28:29], 0, v[154:155]
	s_add_i32 m0, s63, 0x1e000
	s_cmpk_lt_u32 s20, 0x100
	global_load_lds_dwordx4 v[2:3], off
	v_lshlrev_b32_e32 v2, 16, v10
	v_and_b32_e32 v2, 0xfffe0000, v2
	v_lshl_add_u32 v2, v11, 13, v2
	v_and_b32_e32 v3, 1, v10
	v_lshl_or_b32 v2, v3, 6, v2
	v_lshl_add_u32 v160, v12, 1, v2
	v_lshlrev_b32_e32 v2, 16, v14
	v_and_b32_e32 v2, 0xfffe0000, v2
	s_waitcnt vmcnt(6)
	v_lshl_add_u32 v2, v13, 13, v2
	v_and_b32_e32 v3, 1, v14
	v_lshl_or_b32 v2, v3, 6, v2
	v_readlane_b32 s26, v254, 11
	s_cselect_b64 s[48:49], -1, 0
	s_mov_b32 s69, 0
	v_cmp_eq_u32_e64 s[40:41], 0, v17
	v_lshl_or_b32 v184, v17, 3, s21
	v_mov_b32_e32 v161, v1
	v_lshl_add_u32 v162, v15, 1, v2
	v_mov_b32_e32 v163, v1
	v_add_u32_e32 v185, 0, v19
	v_readlane_b32 s20, v255, 59
	s_xor_b32 s21, s26, 24
	s_barrier
	v_readlane_b32 s27, v254, 12
	s_branch .LBB0_619

.LBB0_624:
	s_ashr_i32 s28, s28, 3
	s_add_i32 s28, s33, s28
	s_ashr_i32 s29, s28, 31
	s_lshr_b32 s29, s29, 27
	s_add_i32 s29, s28, s29
	s_ashr_i32 s33, s29, 5
	s_lshl_b32 s33, s33, 3
	s_sub_i32 s36, 0x100, s33
	s_min_i32 s36, s36, 8
	s_abs_i32 s37, s36
	v_cvt_f32_u32_e32 v2, s37
	s_sub_i32 s51, 0, s37
	s_andn2_b32 s29, s29, 31
	s_sub_i32 s28, s28, s29
	v_rcp_iflag_f32_e32 v2, v2
	s_abs_i32 s29, s28
	s_xor_b32 s50, s28, s36
	s_ashr_i32 s50, s50, 31
	v_mul_f32_e32 v2, 0x4f7ffffe, v2
	v_cvt_u32_f32_e32 v2, v2
	s_nop 0
	v_readfirstlane_b32 s52, v2
	s_mul_i32 s51, s51, s52
	s_mul_hi_u32 s51, s52, s51
	s_add_i32 s52, s52, s51
	s_mul_hi_u32 s51, s29, s52
	s_mul_i32 s52, s51, s37
	s_sub_i32 s29, s29, s52
	s_add_i32 s53, s51, 1
	s_sub_i32 s52, s29, s37
	s_cmp_ge_u32 s29, s37
	s_cselect_b32 s51, s53, s51
	s_cselect_b32 s29, s52, s29
	s_add_i32 s52, s51, 1
	s_cmp_ge_u32 s29, s37
	s_cselect_b32 s29, s52, s51
	s_xor_b32 s29, s29, s50
	s_sub_i32 s50, s29, s50
	s_mul_i32 s29, s50, s36
	s_sub_i32 s28, s28, s29
	s_add_i32 s52, s33, s28
	s_xor_b32 s52, s52, 24
